# P0 gain-folding weight transposes (w_in, w_up): 64 loads in flight per item with counted waits instead of load-wait chain
# speedup vs baseline: 1.0046x; 1.0046x over previous
; #define LAS __attribute__((address_space(3)))
; __device__ __forceinline__ void transpose_item(const float* W, int K, int N, bf16_t* WT, int kb, int n0, int src0, LAS float* scr, int lane, const float* gk = nullptr) {
;     const int k0 = 64 * kb;
; #pragma unroll 8
;     for (int i = 0; i < 32; ++i) { const int kk = 2 * i + (lane >> 5); scr[kk * 33 + (lane & 31)] = W[(size_t)(k0 + kk) * N + src0 + (lane & 31)] * (gk ? gk[k0 + kk] : 1.f); }
;     asm volatile("s_waitcnt lgkmcnt(0)" ::: "memory");
.LBB0_25:
	v_lshl_add_u64 v[36:37], v[16:17], 0, s[6:7]
	v_lshl_add_u64 v[50:51], v[34:35], 0, s[6:7]
	s_mov_b64 s[26:27], 0x0
	v_lshl_add_u64 v[56:57], v[32:33], 0, s[26:27]
	global_load_dword v64, v[56:57], off
	v_lshl_add_u64 v[58:59], v[28:29], 0, s[26:27]
	global_load_dword v65, v[58:59], off
	v_lshl_add_u64 v[60:61], v[26:27], 0, s[26:27]
	global_load_dword v66, v[60:61], off
	v_lshl_add_u64 v[62:63], v[24:25], 0, s[26:27]
	global_load_dword v67, v[62:63], off
	v_lshl_add_u64 v[56:57], v[22:23], 0, s[26:27]
	global_load_dword v68, v[56:57], off
	v_lshl_add_u64 v[58:59], v[20:21], 0, s[26:27]
	global_load_dword v69, v[58:59], off
	v_lshl_add_u64 v[60:61], v[18:19], 0, s[26:27]
	global_load_dword v70, v[60:61], off
	v_lshl_add_u64 v[62:63], v[14:15], 0, s[26:27]
	global_load_dword v71, v[62:63], off
	s_mov_b64 s[26:27], 0x58000
	v_lshl_add_u64 v[56:57], v[32:33], 0, s[26:27]
	global_load_dword v72, v[56:57], off
	v_lshl_add_u64 v[58:59], v[28:29], 0, s[26:27]
	global_load_dword v73, v[58:59], off
	v_lshl_add_u64 v[60:61], v[26:27], 0, s[26:27]
	global_load_dword v74, v[60:61], off
	v_lshl_add_u64 v[62:63], v[24:25], 0, s[26:27]
	global_load_dword v75, v[62:63], off
	v_lshl_add_u64 v[56:57], v[22:23], 0, s[26:27]
	global_load_dword v76, v[56:57], off
	v_lshl_add_u64 v[58:59], v[20:21], 0, s[26:27]
	global_load_dword v77, v[58:59], off
	v_lshl_add_u64 v[60:61], v[18:19], 0, s[26:27]
	global_load_dword v78, v[60:61], off
	v_lshl_add_u64 v[62:63], v[14:15], 0, s[26:27]
	global_load_dword v79, v[62:63], off
	s_mov_b64 s[26:27], 0xb0000
	v_lshl_add_u64 v[56:57], v[32:33], 0, s[26:27]
	global_load_dword v80, v[56:57], off
	v_lshl_add_u64 v[58:59], v[28:29], 0, s[26:27]
	global_load_dword v81, v[58:59], off
	v_lshl_add_u64 v[60:61], v[26:27], 0, s[26:27]
	global_load_dword v82, v[60:61], off
	v_lshl_add_u64 v[62:63], v[24:25], 0, s[26:27]
	global_load_dword v83, v[62:63], off
	v_lshl_add_u64 v[56:57], v[22:23], 0, s[26:27]
	global_load_dword v84, v[56:57], off
	v_lshl_add_u64 v[58:59], v[20:21], 0, s[26:27]
	global_load_dword v85, v[58:59], off
	v_lshl_add_u64 v[60:61], v[18:19], 0, s[26:27]
	global_load_dword v86, v[60:61], off
	v_lshl_add_u64 v[62:63], v[14:15], 0, s[26:27]
	global_load_dword v87, v[62:63], off
	s_mov_b64 s[26:27], 0x108000
	v_lshl_add_u64 v[56:57], v[32:33], 0, s[26:27]
	global_load_dword v88, v[56:57], off
	v_lshl_add_u64 v[58:59], v[28:29], 0, s[26:27]
	global_load_dword v89, v[58:59], off
	v_lshl_add_u64 v[60:61], v[26:27], 0, s[26:27]
	global_load_dword v90, v[60:61], off
	v_lshl_add_u64 v[62:63], v[24:25], 0, s[26:27]
	global_load_dword v91, v[62:63], off
	v_lshl_add_u64 v[56:57], v[22:23], 0, s[26:27]
	global_load_dword v92, v[56:57], off
	v_lshl_add_u64 v[58:59], v[20:21], 0, s[26:27]
	global_load_dword v93, v[58:59], off
	v_lshl_add_u64 v[60:61], v[18:19], 0, s[26:27]
	global_load_dword v94, v[60:61], off
	v_lshl_add_u64 v[62:63], v[14:15], 0, s[26:27]
	global_load_dword v95, v[62:63], off
	s_and_b64 vcc, exec, s[28:29]
	s_cbranch_vccz P0T1_nogain
	global_load_dword v96, v[50:51], off
	global_load_dword v97, v[36:37], off offset:8
	global_load_dword v98, v[36:37], off offset:16
	global_load_dword v99, v[36:37], off offset:24
	global_load_dword v100, v[36:37], off offset:32
	global_load_dword v101, v[36:37], off offset:40
	global_load_dword v102, v[36:37], off offset:48
	global_load_dword v103, v[36:37], off offset:56
	global_load_dword v104, v[50:51], off offset:64
	global_load_dword v105, v[36:37], off offset:72
	global_load_dword v106, v[36:37], off offset:80
	global_load_dword v107, v[36:37], off offset:88
	global_load_dword v108, v[36:37], off offset:96
	global_load_dword v109, v[36:37], off offset:104
	global_load_dword v110, v[36:37], off offset:112
	global_load_dword v111, v[36:37], off offset:120
	global_load_dword v112, v[50:51], off offset:128
	global_load_dword v113, v[36:37], off offset:136
	global_load_dword v114, v[36:37], off offset:144
	global_load_dword v115, v[36:37], off offset:152
	global_load_dword v116, v[36:37], off offset:160
	global_load_dword v117, v[36:37], off offset:168
	global_load_dword v118, v[36:37], off offset:176
	global_load_dword v119, v[36:37], off offset:184
	global_load_dword v120, v[50:51], off offset:192
	global_load_dword v121, v[36:37], off offset:200
	global_load_dword v122, v[36:37], off offset:208
	global_load_dword v123, v[36:37], off offset:216
	global_load_dword v124, v[36:37], off offset:224
	global_load_dword v125, v[36:37], off offset:232
	global_load_dword v126, v[36:37], off offset:240
	global_load_dword v127, v[36:37], off offset:248
	s_branch P0T1_join
; #define LAS __attribute__((address_space(3)))
; __device__ __forceinline__ void transpose_item(const float* W, int K, int N, bf16_t* WT, int kb, int n0, int src0, LAS float* scr, int lane, const float* gk = nullptr) {
;     const int k0 = 64 * kb;
; #pragma unroll 8
;     for (int i = 0; i < 32; ++i) { const int kk = 2 * i + (lane >> 5); scr[kk * 33 + (lane & 31)] = W[(size_t)(k0 + kk) * N + src0 + (lane & 31)] * (gk ? gk[k0 + kk] : 1.f); }
;     asm volatile("s_waitcnt lgkmcnt(0)" ::: "memory");
P0T1_nogain:
	v_mov_b32_e32 v96, 1.0
	v_mov_b32_e32 v97, 1.0
	v_mov_b32_e32 v98, 1.0
	v_mov_b32_e32 v99, 1.0
	v_mov_b32_e32 v100, 1.0
	v_mov_b32_e32 v101, 1.0
	v_mov_b32_e32 v102, 1.0
	v_mov_b32_e32 v103, 1.0
	v_mov_b32_e32 v104, 1.0
	v_mov_b32_e32 v105, 1.0
	v_mov_b32_e32 v106, 1.0
	v_mov_b32_e32 v107, 1.0
	v_mov_b32_e32 v108, 1.0
	v_mov_b32_e32 v109, 1.0
	v_mov_b32_e32 v110, 1.0
	v_mov_b32_e32 v111, 1.0
	v_mov_b32_e32 v112, 1.0
	v_mov_b32_e32 v113, 1.0
	v_mov_b32_e32 v114, 1.0
	v_mov_b32_e32 v115, 1.0
	v_mov_b32_e32 v116, 1.0
	v_mov_b32_e32 v117, 1.0
	v_mov_b32_e32 v118, 1.0
	v_mov_b32_e32 v119, 1.0
	v_mov_b32_e32 v120, 1.0
	v_mov_b32_e32 v121, 1.0
	v_mov_b32_e32 v122, 1.0
	v_mov_b32_e32 v123, 1.0
	v_mov_b32_e32 v124, 1.0
	v_mov_b32_e32 v125, 1.0
	v_mov_b32_e32 v126, 1.0
	v_mov_b32_e32 v127, 1.0
	s_waitcnt vmcnt(0)
P0T1_join:
	s_waitcnt vmcnt(24)
	v_mul_f32_e32 v64, v64, v96
	ds_write_b32 v3, v64
	v_mul_f32_e32 v65, v65, v97
	ds_write_b32 v3, v65 offset:264
	v_mul_f32_e32 v66, v66, v98
	ds_write_b32 v3, v66 offset:528
	v_mul_f32_e32 v67, v67, v99
	ds_write_b32 v3, v67 offset:792
	v_mul_f32_e32 v68, v68, v100
	ds_write_b32 v3, v68 offset:1056
	v_mul_f32_e32 v69, v69, v101
	ds_write_b32 v3, v69 offset:1320
	v_mul_f32_e32 v70, v70, v102
	ds_write_b32 v3, v70 offset:1584
	v_mul_f32_e32 v71, v71, v103
	ds_write_b32 v3, v71 offset:1848
	s_waitcnt vmcnt(16)
	v_mul_f32_e32 v72, v72, v104
	ds_write_b32 v3, v72 offset:2112
	v_mul_f32_e32 v73, v73, v105
	ds_write_b32 v3, v73 offset:2376
	v_mul_f32_e32 v74, v74, v106
	ds_write_b32 v3, v74 offset:2640
	v_mul_f32_e32 v75, v75, v107
	ds_write_b32 v3, v75 offset:2904
	v_mul_f32_e32 v76, v76, v108
	ds_write_b32 v3, v76 offset:3168
	v_mul_f32_e32 v77, v77, v109
	ds_write_b32 v3, v77 offset:3432
	v_mul_f32_e32 v78, v78, v110
	ds_write_b32 v3, v78 offset:3696
	v_mul_f32_e32 v79, v79, v111
	ds_write_b32 v3, v79 offset:3960
	s_waitcnt vmcnt(8)
	v_mul_f32_e32 v80, v80, v112
	ds_write_b32 v3, v80 offset:4224
	v_mul_f32_e32 v81, v81, v113
	ds_write_b32 v3, v81 offset:4488
	v_mul_f32_e32 v82, v82, v114
	ds_write_b32 v3, v82 offset:4752
	v_mul_f32_e32 v83, v83, v115
	ds_write_b32 v3, v83 offset:5016
	v_mul_f32_e32 v84, v84, v116
	ds_write_b32 v3, v84 offset:5280
	v_mul_f32_e32 v85, v85, v117
	ds_write_b32 v3, v85 offset:5544
	v_mul_f32_e32 v86, v86, v118
	ds_write_b32 v3, v86 offset:5808
	v_mul_f32_e32 v87, v87, v119
	ds_write_b32 v3, v87 offset:6072
	s_waitcnt vmcnt(0)
	v_mul_f32_e32 v88, v88, v120
	ds_write_b32 v3, v88 offset:6336
	v_mul_f32_e32 v89, v89, v121
	ds_write_b32 v3, v89 offset:6600
	v_mul_f32_e32 v90, v90, v122
	ds_write_b32 v3, v90 offset:6864
	v_mul_f32_e32 v91, v91, v123
	ds_write_b32 v3, v91 offset:7128
	v_mul_f32_e32 v92, v92, v124
	ds_write_b32 v3, v92 offset:7392
	v_mul_f32_e32 v93, v93, v125
	ds_write_b32 v3, v93 offset:7656
	v_mul_f32_e32 v94, v94, v126
	ds_write_b32 v3, v94 offset:7920
	v_mul_f32_e32 v95, v95, v127
	ds_write_b32 v3, v95 offset:8184
	s_branch .LBB0_42

; #define LAS __attribute__((address_space(3)))
; __device__ __forceinline__ void transpose_item(const float* W, int K, int N, bf16_t* WT, int kb, int n0, int src0, LAS float* scr, int lane, const float* gk = nullptr) {
;     const int k0 = 64 * kb;
; #pragma unroll 8
;     for (int i = 0; i < 32; ++i) { const int kk = 2 * i + (lane >> 5); scr[kk * 33 + (lane & 31)] = W[(size_t)(k0 + kk) * N + src0 + (lane & 31)] * (gk ? gk[k0 + kk] : 1.f); }
;     asm volatile("s_waitcnt lgkmcnt(0)" ::: "memory");
.LBB0_53:
	v_add_u32_e32 v129, 0, v16
	v_mad_i64_i32 v[56:57], s[40:41], v129, s31, v[14:15]
	global_load_dword v64, v[56:57], off
	v_add_u32_e32 v130, 2, v16
	v_mad_i64_i32 v[58:59], s[40:41], v130, s31, v[14:15]
	global_load_dword v65, v[58:59], off
	v_add_u32_e32 v131, 4, v16
	v_mad_i64_i32 v[60:61], s[40:41], v131, s31, v[14:15]
	global_load_dword v66, v[60:61], off
	v_add_u32_e32 v128, 6, v16
	v_mad_i64_i32 v[62:63], s[40:41], v128, s31, v[14:15]
	global_load_dword v67, v[62:63], off
	v_add_u32_e32 v129, 8, v16
	v_mad_i64_i32 v[56:57], s[40:41], v129, s31, v[14:15]
	global_load_dword v68, v[56:57], off
	v_add_u32_e32 v130, 10, v16
	v_mad_i64_i32 v[58:59], s[40:41], v130, s31, v[14:15]
	global_load_dword v69, v[58:59], off
	v_add_u32_e32 v131, 12, v16
	v_mad_i64_i32 v[60:61], s[40:41], v131, s31, v[14:15]
	global_load_dword v70, v[60:61], off
	v_add_u32_e32 v128, 14, v16
	v_mad_i64_i32 v[62:63], s[40:41], v128, s31, v[14:15]
	global_load_dword v71, v[62:63], off
	v_add_u32_e32 v129, 16, v16
	v_mad_i64_i32 v[56:57], s[40:41], v129, s31, v[14:15]
	global_load_dword v72, v[56:57], off
	v_add_u32_e32 v130, 18, v16
	v_mad_i64_i32 v[58:59], s[40:41], v130, s31, v[14:15]
	global_load_dword v73, v[58:59], off
	v_add_u32_e32 v131, 20, v16
	v_mad_i64_i32 v[60:61], s[40:41], v131, s31, v[14:15]
	global_load_dword v74, v[60:61], off
	v_add_u32_e32 v128, 22, v16
	v_mad_i64_i32 v[62:63], s[40:41], v128, s31, v[14:15]
	global_load_dword v75, v[62:63], off
	v_add_u32_e32 v129, 24, v16
	v_mad_i64_i32 v[56:57], s[40:41], v129, s31, v[14:15]
	global_load_dword v76, v[56:57], off
	v_add_u32_e32 v130, 26, v16
	v_mad_i64_i32 v[58:59], s[40:41], v130, s31, v[14:15]
	global_load_dword v77, v[58:59], off
	v_add_u32_e32 v131, 28, v16
	v_mad_i64_i32 v[60:61], s[40:41], v131, s31, v[14:15]
	global_load_dword v78, v[60:61], off
	v_add_u32_e32 v128, 30, v16
	v_mad_i64_i32 v[62:63], s[40:41], v128, s31, v[14:15]
	global_load_dword v79, v[62:63], off
	v_add_u32_e32 v129, 32, v16
	v_mad_i64_i32 v[56:57], s[40:41], v129, s31, v[14:15]
	global_load_dword v80, v[56:57], off
	v_add_u32_e32 v130, 34, v16
	v_mad_i64_i32 v[58:59], s[40:41], v130, s31, v[14:15]
	global_load_dword v81, v[58:59], off
	v_add_u32_e32 v131, 36, v16
	v_mad_i64_i32 v[60:61], s[40:41], v131, s31, v[14:15]
	global_load_dword v82, v[60:61], off
	v_add_u32_e32 v128, 38, v16
	v_mad_i64_i32 v[62:63], s[40:41], v128, s31, v[14:15]
	global_load_dword v83, v[62:63], off
	v_add_u32_e32 v129, 40, v16
	v_mad_i64_i32 v[56:57], s[40:41], v129, s31, v[14:15]
	global_load_dword v84, v[56:57], off
	v_add_u32_e32 v130, 42, v16
	v_mad_i64_i32 v[58:59], s[40:41], v130, s31, v[14:15]
	global_load_dword v85, v[58:59], off
	v_add_u32_e32 v131, 44, v16
	v_mad_i64_i32 v[60:61], s[40:41], v131, s31, v[14:15]
	global_load_dword v86, v[60:61], off
	v_add_u32_e32 v128, 46, v16
	v_mad_i64_i32 v[62:63], s[40:41], v128, s31, v[14:15]
	global_load_dword v87, v[62:63], off
	v_add_u32_e32 v129, 48, v16
	v_mad_i64_i32 v[56:57], s[40:41], v129, s31, v[14:15]
	global_load_dword v88, v[56:57], off
	v_add_u32_e32 v130, 50, v16
	v_mad_i64_i32 v[58:59], s[40:41], v130, s31, v[14:15]
	global_load_dword v89, v[58:59], off
	v_add_u32_e32 v131, 52, v16
	v_mad_i64_i32 v[60:61], s[40:41], v131, s31, v[14:15]
	global_load_dword v90, v[60:61], off
	v_add_u32_e32 v128, 54, v16
	v_mad_i64_i32 v[62:63], s[40:41], v128, s31, v[14:15]
	global_load_dword v91, v[62:63], off
	v_add_u32_e32 v129, 56, v16
	v_mad_i64_i32 v[56:57], s[40:41], v129, s31, v[14:15]
	global_load_dword v92, v[56:57], off
	v_add_u32_e32 v130, 58, v16
	v_mad_i64_i32 v[58:59], s[40:41], v130, s31, v[14:15]
	global_load_dword v93, v[58:59], off
	v_add_u32_e32 v131, 60, v16
	v_mad_i64_i32 v[60:61], s[40:41], v131, s31, v[14:15]
	global_load_dword v94, v[60:61], off
	v_add_u32_e32 v128, 62, v16
	v_mad_i64_i32 v[62:63], s[40:41], v128, s31, v[14:15]
	global_load_dword v95, v[62:63], off
	s_and_b64 vcc, exec, s[26:27]
	s_cbranch_vccz P0T2_nogain
	global_load_dword v96, v[18:19], off offset:-56
	global_load_dword v97, v[18:19], off offset:-48
	global_load_dword v98, v[18:19], off offset:-40
	global_load_dword v99, v[18:19], off offset:-32
	global_load_dword v100, v[18:19], off offset:-24
	global_load_dword v101, v[18:19], off offset:-16
	global_load_dword v102, v[18:19], off offset:-8
	global_load_dword v103, v[18:19], off
	global_load_dword v104, v[18:19], off offset:8
	global_load_dword v105, v[18:19], off offset:16
	global_load_dword v106, v[18:19], off offset:24
	global_load_dword v107, v[18:19], off offset:32
	global_load_dword v108, v[18:19], off offset:40
	global_load_dword v109, v[18:19], off offset:48
	global_load_dword v110, v[18:19], off offset:56
	global_load_dword v111, v[18:19], off offset:64
	global_load_dword v112, v[18:19], off offset:72
	global_load_dword v113, v[18:19], off offset:80
	global_load_dword v114, v[18:19], off offset:88
	global_load_dword v115, v[18:19], off offset:96
	global_load_dword v116, v[18:19], off offset:104
	global_load_dword v117, v[18:19], off offset:112
	global_load_dword v118, v[18:19], off offset:120
	global_load_dword v119, v[18:19], off offset:128
	global_load_dword v120, v[18:19], off offset:136
	global_load_dword v121, v[18:19], off offset:144
	global_load_dword v122, v[18:19], off offset:152
	global_load_dword v123, v[18:19], off offset:160
	global_load_dword v124, v[18:19], off offset:168
	global_load_dword v125, v[18:19], off offset:176
	global_load_dword v126, v[18:19], off offset:184
	global_load_dword v127, v[18:19], off offset:192
	s_branch P0T2_join
; #define LAS __attribute__((address_space(3)))
; __device__ __forceinline__ void transpose_item(const float* W, int K, int N, bf16_t* WT, int kb, int n0, int src0, LAS float* scr, int lane, const float* gk = nullptr) {
;     const int k0 = 64 * kb;
; #pragma unroll 8
;     for (int i = 0; i < 32; ++i) { const int kk = 2 * i + (lane >> 5); scr[kk * 33 + (lane & 31)] = W[(size_t)(k0 + kk) * N + src0 + (lane & 31)] * (gk ? gk[k0 + kk] : 1.f); }
;     asm volatile("s_waitcnt lgkmcnt(0)" ::: "memory");
P0T2_nogain:
	v_mov_b32_e32 v96, 1.0
	v_mov_b32_e32 v97, 1.0
	v_mov_b32_e32 v98, 1.0
	v_mov_b32_e32 v99, 1.0
	v_mov_b32_e32 v100, 1.0
	v_mov_b32_e32 v101, 1.0
	v_mov_b32_e32 v102, 1.0
	v_mov_b32_e32 v103, 1.0
	v_mov_b32_e32 v104, 1.0
	v_mov_b32_e32 v105, 1.0
	v_mov_b32_e32 v106, 1.0
	v_mov_b32_e32 v107, 1.0
	v_mov_b32_e32 v108, 1.0
	v_mov_b32_e32 v109, 1.0
	v_mov_b32_e32 v110, 1.0
	v_mov_b32_e32 v111, 1.0
	v_mov_b32_e32 v112, 1.0
	v_mov_b32_e32 v113, 1.0
	v_mov_b32_e32 v114, 1.0
	v_mov_b32_e32 v115, 1.0
	v_mov_b32_e32 v116, 1.0
	v_mov_b32_e32 v117, 1.0
	v_mov_b32_e32 v118, 1.0
	v_mov_b32_e32 v119, 1.0
	v_mov_b32_e32 v120, 1.0
	v_mov_b32_e32 v121, 1.0
	v_mov_b32_e32 v122, 1.0
	v_mov_b32_e32 v123, 1.0
	v_mov_b32_e32 v124, 1.0
	v_mov_b32_e32 v125, 1.0
	v_mov_b32_e32 v126, 1.0
	v_mov_b32_e32 v127, 1.0
	s_waitcnt vmcnt(0)
P0T2_join:
	s_waitcnt vmcnt(24)
	v_mul_f32_e32 v64, v64, v96
	ds_write_b32 v3, v64
	v_mul_f32_e32 v65, v65, v97
	ds_write_b32 v3, v65 offset:264
	v_mul_f32_e32 v66, v66, v98
	ds_write_b32 v3, v66 offset:528
	v_mul_f32_e32 v67, v67, v99
	ds_write_b32 v3, v67 offset:792
	v_mul_f32_e32 v68, v68, v100
	ds_write_b32 v3, v68 offset:1056
	v_mul_f32_e32 v69, v69, v101
	ds_write_b32 v3, v69 offset:1320
	v_mul_f32_e32 v70, v70, v102
	ds_write_b32 v3, v70 offset:1584
	v_mul_f32_e32 v71, v71, v103
	ds_write_b32 v3, v71 offset:1848
	s_waitcnt vmcnt(16)
	v_mul_f32_e32 v72, v72, v104
	ds_write_b32 v3, v72 offset:2112
	v_mul_f32_e32 v73, v73, v105
	ds_write_b32 v3, v73 offset:2376
	v_mul_f32_e32 v74, v74, v106
	ds_write_b32 v3, v74 offset:2640
	v_mul_f32_e32 v75, v75, v107
	ds_write_b32 v3, v75 offset:2904
	v_mul_f32_e32 v76, v76, v108
	ds_write_b32 v3, v76 offset:3168
	v_mul_f32_e32 v77, v77, v109
	ds_write_b32 v3, v77 offset:3432
	v_mul_f32_e32 v78, v78, v110
	ds_write_b32 v3, v78 offset:3696
	v_mul_f32_e32 v79, v79, v111
	ds_write_b32 v3, v79 offset:3960
	s_waitcnt vmcnt(8)
	v_mul_f32_e32 v80, v80, v112
	ds_write_b32 v3, v80 offset:4224
	v_mul_f32_e32 v81, v81, v113
	ds_write_b32 v3, v81 offset:4488
	v_mul_f32_e32 v82, v82, v114
	ds_write_b32 v3, v82 offset:4752
	v_mul_f32_e32 v83, v83, v115
	ds_write_b32 v3, v83 offset:5016
	v_mul_f32_e32 v84, v84, v116
	ds_write_b32 v3, v84 offset:5280
	v_mul_f32_e32 v85, v85, v117
	ds_write_b32 v3, v85 offset:5544
	v_mul_f32_e32 v86, v86, v118
	ds_write_b32 v3, v86 offset:5808
	v_mul_f32_e32 v87, v87, v119
	ds_write_b32 v3, v87 offset:6072
	s_waitcnt vmcnt(0)
	v_mul_f32_e32 v88, v88, v120
	ds_write_b32 v3, v88 offset:6336
	v_mul_f32_e32 v89, v89, v121
	ds_write_b32 v3, v89 offset:6600
	v_mul_f32_e32 v90, v90, v122
	ds_write_b32 v3, v90 offset:6864
	v_mul_f32_e32 v91, v91, v123
	ds_write_b32 v3, v91 offset:7128
	v_mul_f32_e32 v92, v92, v124
	ds_write_b32 v3, v92 offset:7392
	v_mul_f32_e32 v93, v93, v125
	ds_write_b32 v3, v93 offset:7656
	v_mul_f32_e32 v94, v94, v126
	ds_write_b32 v3, v94 offset:7920
	v_mul_f32_e32 v95, v95, v127
	ds_write_b32 v3, v95 offset:8184
	v_add_u32_e32 v3, 0x2100, v3
	s_branch .LBB0_8
